# v14 + pool phase loads with default cache policy (trailing-window re-reads can hit L2)
# baseline (speedup 1.0000x reference)
.LBB0_312:
	s_add_i32 s25, s25, 1
	s_cmp_lt_u32 s9, s25
	s_cbranch_scc1 .LBB0_311
	global_load_dwordx4 v[34:37], v[12:13], off
	s_waitcnt vmcnt(0)
	v_lshlrev_b32_e32 v14, 16, v34
	v_and_b32_e32 v15, 0xffff0000, v34
	v_lshlrev_b32_e32 v24, 16, v35
	v_and_b32_e32 v25, 0xffff0000, v35
	v_lshlrev_b32_e32 v34, 16, v36
	v_and_b32_e32 v35, 0xffff0000, v36
	v_lshlrev_b32_e32 v36, 16, v37
	v_and_b32_e32 v37, 0xffff0000, v37
	v_pk_add_f32 v[26:27], v[26:27], v[14:15]
	v_pk_add_f32 v[28:29], v[28:29], v[24:25]
	v_pk_add_f32 v[30:31], v[30:31], v[34:35]
	v_pk_add_f32 v[32:33], v[32:33], v[36:37]
	s_branch .LBB0_311

.LBB0_316:
	s_or_b64 exec, exec, s[60:61]
	s_lshl_b64 s[10:11], s[10:11], 12
	s_lshl_b64 s[10:11], s[10:11], 1
	v_lshl_add_u64 v[40:41], v[20:21], 0, s[10:11]
	global_load_dwordx4 v[46:49], v[40:41], off
	s_add_i32 s33, s33, 4
	v_cvt_f32_u32_e32 v52, s33
	s_waitcnt vmcnt(2)
	v_lshlrev_b32_e32 v40, 16, v12
	v_and_b32_e32 v41, 0xffff0000, v12
	v_lshlrev_b32_e32 v12, 16, v13
	v_and_b32_e32 v13, 0xffff0000, v13
	v_pk_add_f32 v[34:35], v[12:13], v[34:35] neg_lo:[0,1] neg_hi:[0,1]
	v_cmp_lt_i32_e32 vcc, s33, v43
	v_lshlrev_b32_e32 v50, 16, v14
	v_and_b32_e32 v51, 0xffff0000, v14
	v_pk_add_f32 v[28:29], v[28:29], v[34:35]
	v_cndmask_b32_e32 v34, v44, v52, vcc
	v_pk_add_f32 v[36:37], v[50:51], v[36:37] neg_lo:[0,1] neg_hi:[0,1]
	v_div_scale_f32 v35, s[60:61], v34, v34, 1.0
	v_pk_add_f32 v[30:31], v[30:31], v[36:37]
	v_rcp_f32_e32 v36, v35
	v_lshlrev_b32_e32 v14, 16, v15
	v_and_b32_e32 v15, 0xffff0000, v15
	v_pk_add_f32 v[38:39], v[14:15], v[38:39] neg_lo:[0,1] neg_hi:[0,1]
	v_div_scale_f32 v37, vcc, 1.0, v34, 1.0
	v_pk_add_f32 v[32:33], v[32:33], v[38:39]
	v_fma_f32 v38, -v35, v36, 1.0
	v_fmac_f32_e32 v36, v38, v36
	v_mul_f32_e32 v38, v37, v36
	v_fma_f32 v39, -v35, v38, v37
	v_fmac_f32_e32 v38, v39, v36
	v_fma_f32 v35, -v35, v38, v37
	v_pk_add_f32 v[24:25], v[40:41], v[24:25] neg_lo:[0,1] neg_hi:[0,1]
	v_div_fmas_f32 v35, v35, v36, v38
	v_pk_add_f32 v[26:27], v[26:27], v[24:25]
	v_div_fixup_f32 v34, v35, v34, 1.0
	v_fma_f32 v35, v34, v26, -v40
	v_fma_f32 v36, v34, v27, -v41
	v_fma_f32 v13, v34, v29, -v13
	v_fma_f32 v37, v34, v30, -v50
	v_fma_f32 v38, v34, v31, -v51
	v_fma_f32 v15, v34, v33, -v15
	s_add_i32 s25, s25, 4
	v_fma_f32 v12, v34, v28, -v12
	v_fma_f32 v14, v34, v32, -v14
	v_mul_f32_e32 v34, v4, v35
	v_mul_f32_e32 v35, v5, v36
	v_mul_f32_e32 v13, v7, v13
	v_mul_f32_e32 v36, v8, v37
	v_mul_f32_e32 v37, v9, v38
	v_mul_f32_e32 v15, v11, v15
	v_lshl_add_u64 v[24:25], v[18:19], 0, s[10:11]
	v_mul_f32_e32 v12, v6, v12
	v_mul_f32_e32 v14, v10, v14
	s_cmp_eq_u32 s25, 64
	s_waitcnt vmcnt(0)
	v_lshlrev_b32_e32 v38, 16, v46
	v_and_b32_e32 v39, 0xffff0000, v46
	v_lshlrev_b32_e32 v40, 16, v47
	v_and_b32_e32 v41, 0xffff0000, v47
	v_lshlrev_b32_e32 v46, 16, v48
	v_and_b32_e32 v47, 0xffff0000, v48
	v_lshlrev_b32_e32 v48, 16, v49
	v_and_b32_e32 v49, 0xffff0000, v49
	v_mul_f32_e32 v13, v13, v41
	v_mul_f32_e32 v15, v15, v49
	v_mul_f32_e32 v34, v34, v38
	v_mul_f32_e32 v35, v35, v39
	v_mul_f32_e32 v38, v12, v40
	v_mul_f32_e32 v36, v36, v46
	v_mul_f32_e32 v37, v37, v47
	v_mul_f32_e32 v39, v14, v48
	v_cvt_pk_bf16_f32 v12, v34, v35
	v_cvt_pk_bf16_f32 v13, v38, v13
	v_cvt_pk_bf16_f32 v14, v36, v37
	v_cvt_pk_bf16_f32 v15, v39, v15
	global_store_dwordx4 v[24:25], v[12:15], off
	s_cbranch_scc1 .LBB0_308
.LBB0_317:
	s_add_i32 s10, s8, s25
	s_ashr_i32 s11, s10, 31
	s_lshl_b64 s[60:61], s[10:11], 13
	v_lshl_add_u64 v[12:13], v[16:17], 0, s[60:61]
	global_load_dwordx4 v[12:15], v[12:13], off
	s_add_i32 s33, s9, s25
	v_cmp_ge_i32_e32 vcc, s33, v43
	v_mov_b32_e32 v24, 0
	v_mov_b32_e32 v34, 0
	v_mov_b32_e32 v35, 0
	v_mov_b32_e32 v36, 0
	v_mov_b32_e32 v37, 0
	v_mov_b32_e32 v38, 0
	v_mov_b32_e32 v39, 0
	v_mov_b32_e32 v40, 0
	v_mov_b32_e32 v41, 0
	s_and_saveexec_b64 s[60:61], vcc
	s_cbranch_execz .LBB0_319
	v_add_u32_e32 v34, s25, v45
	v_ashrrev_i32_e32 v35, 31, v34
	v_lshlrev_b64 v[34:35], 13, v[34:35]
	v_lshl_add_u64 v[34:35], v[16:17], 0, v[34:35]
	global_load_dwordx4 v[38:41], v[34:35], off
	s_waitcnt vmcnt(0)
	v_lshlrev_b32_e32 v34, 16, v38
	v_and_b32_e32 v35, 0xffff0000, v38
	v_lshlrev_b32_e32 v36, 16, v39
	v_and_b32_e32 v37, 0xffff0000, v39
	v_lshlrev_b32_e32 v38, 16, v40
	v_and_b32_e32 v39, 0xffff0000, v40
	v_lshlrev_b32_e32 v40, 16, v41
	v_and_b32_e32 v41, 0xffff0000, v41
.LBB0_319:
	s_or_b64 exec, exec, s[60:61]
	s_lshl_b64 s[60:61], s[10:11], 12
	s_lshl_b64 s[60:61], s[60:61], 1
	v_lshl_add_u64 v[46:47], v[20:21], 0, s[60:61]
	global_load_dwordx4 v[46:49], v[46:47], off
	s_add_i32 s11, s33, 1
	v_cvt_f32_u32_e32 v25, s11
	s_waitcnt vmcnt(1)
	v_lshlrev_b32_e32 v50, 16, v12
	v_and_b32_e32 v51, 0xffff0000, v12
	v_cmp_lt_i32_e32 vcc, s11, v43
	v_pk_add_f32 v[34:35], v[50:51], v[34:35] neg_lo:[0,1] neg_hi:[0,1]
	v_lshlrev_b32_e32 v12, 16, v13
	v_cndmask_b32_e32 v25, v44, v25, vcc
	v_pk_add_f32 v[26:27], v[26:27], v[34:35]
	v_div_scale_f32 v34, s[66:67], v25, v25, 1.0
	v_rcp_f32_e32 v35, v34
	v_and_b32_e32 v13, 0xffff0000, v13
	v_pk_add_f32 v[36:37], v[12:13], v[36:37] neg_lo:[0,1] neg_hi:[0,1]
	v_lshlrev_b32_e32 v52, 16, v14
	v_pk_add_f32 v[28:29], v[28:29], v[36:37]
	v_fma_f32 v37, -v34, v35, 1.0
	v_and_b32_e32 v53, 0xffff0000, v14
	v_lshlrev_b32_e32 v14, 16, v15
	v_and_b32_e32 v15, 0xffff0000, v15
	v_div_scale_f32 v36, vcc, 1.0, v25, 1.0
	v_fmac_f32_e32 v35, v37, v35
	v_pk_add_f32 v[40:41], v[14:15], v[40:41] neg_lo:[0,1] neg_hi:[0,1]
	v_mul_f32_e32 v37, v36, v35
	v_pk_add_f32 v[32:33], v[32:33], v[40:41]
	v_fma_f32 v40, -v34, v37, v36
	v_fmac_f32_e32 v37, v40, v35
	v_fma_f32 v34, -v34, v37, v36
	v_pk_add_f32 v[38:39], v[52:53], v[38:39] neg_lo:[0,1] neg_hi:[0,1]
	v_div_fmas_f32 v34, v34, v35, v37
	s_add_i32 s62, s10, 1
	v_pk_add_f32 v[30:31], v[30:31], v[38:39]
	v_div_fixup_f32 v25, v34, v25, 1.0
	s_ashr_i32 s63, s62, 31
	v_fma_f32 v34, v25, v26, -v50
	v_fma_f32 v35, v25, v27, -v51
	v_fma_f32 v12, v25, v28, -v12
	v_fma_f32 v13, v25, v29, -v13
	v_fma_f32 v36, v25, v30, -v52
	v_fma_f32 v37, v25, v31, -v53
	v_fma_f32 v14, v25, v32, -v14
	v_fma_f32 v15, v25, v33, -v15
	s_lshl_b64 s[64:65], s[62:63], 13
	v_mul_f32_e32 v25, v4, v34
	v_mul_f32_e32 v34, v5, v35
	v_mul_f32_e32 v12, v6, v12
	v_mul_f32_e32 v13, v7, v13
	v_mul_f32_e32 v35, v8, v36
	v_mul_f32_e32 v36, v9, v37
	v_mul_f32_e32 v14, v10, v14
	v_mul_f32_e32 v15, v11, v15
	v_lshl_add_u64 v[38:39], v[16:17], 0, s[64:65]
	v_cmp_ge_i32_e32 vcc, s11, v43
	s_waitcnt vmcnt(0)
	v_lshlrev_b32_e32 v37, 16, v46
	v_and_b32_e32 v40, 0xffff0000, v46
	v_lshlrev_b32_e32 v41, 16, v47
	v_and_b32_e32 v46, 0xffff0000, v47
	v_lshlrev_b32_e32 v47, 16, v48
	v_and_b32_e32 v48, 0xffff0000, v48
	v_lshlrev_b32_e32 v50, 16, v49
	v_and_b32_e32 v49, 0xffff0000, v49
	v_mul_f32_e32 v25, v25, v37
	v_mul_f32_e32 v34, v34, v40
	v_mul_f32_e32 v12, v12, v41
	v_mul_f32_e32 v13, v13, v46
	v_mul_f32_e32 v37, v35, v47
	v_mul_f32_e32 v36, v36, v48
	v_mul_f32_e32 v14, v14, v50
	v_mul_f32_e32 v15, v15, v49
	v_cvt_pk_bf16_f32 v34, v25, v34
	v_cvt_pk_bf16_f32 v35, v12, v13
	v_cvt_pk_bf16_f32 v36, v37, v36
	v_cvt_pk_bf16_f32 v37, v14, v15
	global_load_dwordx4 v[12:15], v[38:39], off
	v_lshl_add_u64 v[38:39], v[18:19], 0, s[60:61]
	global_store_dwordx4 v[38:39], v[34:37], off
	v_mov_b32_e32 v25, 0
	v_mov_b32_e32 v38, 0
	v_mov_b32_e32 v34, 0
	v_mov_b32_e32 v35, 0
	v_mov_b32_e32 v36, 0
	v_mov_b32_e32 v37, 0
	v_mov_b32_e32 v39, 0
	s_and_saveexec_b64 s[60:61], vcc
	s_cbranch_execz .LBB0_321
	v_add3_u32 v24, v45, s25, 1
	v_ashrrev_i32_e32 v25, 31, v24
	v_lshlrev_b64 v[24:25], 13, v[24:25]
	v_lshl_add_u64 v[24:25], v[16:17], 0, v[24:25]
	global_load_dwordx4 v[36:39], v[24:25], off
	s_waitcnt vmcnt(0)
	v_lshlrev_b32_e32 v24, 16, v36
	v_and_b32_e32 v25, 0xffff0000, v36
	v_lshlrev_b32_e32 v34, 16, v37
	v_and_b32_e32 v35, 0xffff0000, v37
	v_lshlrev_b32_e32 v36, 16, v38
	v_and_b32_e32 v37, 0xffff0000, v38
	v_lshlrev_b32_e32 v38, 16, v39
	v_and_b32_e32 v39, 0xffff0000, v39
.LBB0_321:
	s_or_b64 exec, exec, s[60:61]
	s_lshl_b64 s[60:61], s[62:63], 12
	s_lshl_b64 s[60:61], s[60:61], 1
	v_lshl_add_u64 v[40:41], v[20:21], 0, s[60:61]
	global_load_dwordx4 v[46:49], v[40:41], off
	s_add_i32 s11, s33, 2
	v_cvt_f32_u32_e32 v52, s11
	s_waitcnt vmcnt(2)
	v_lshlrev_b32_e32 v40, 16, v12
	v_and_b32_e32 v41, 0xffff0000, v12
	v_lshlrev_b32_e32 v12, 16, v13
	v_and_b32_e32 v13, 0xffff0000, v13
	v_pk_add_f32 v[34:35], v[12:13], v[34:35] neg_lo:[0,1] neg_hi:[0,1]
	v_cmp_lt_i32_e32 vcc, s11, v43
	v_lshlrev_b32_e32 v50, 16, v14
	v_and_b32_e32 v51, 0xffff0000, v14
	v_pk_add_f32 v[28:29], v[28:29], v[34:35]
	v_cndmask_b32_e32 v34, v44, v52, vcc
	v_pk_add_f32 v[36:37], v[50:51], v[36:37] neg_lo:[0,1] neg_hi:[0,1]
	v_div_scale_f32 v35, s[66:67], v34, v34, 1.0
	v_pk_add_f32 v[30:31], v[30:31], v[36:37]
	v_rcp_f32_e32 v36, v35
	v_lshlrev_b32_e32 v14, 16, v15
	v_and_b32_e32 v15, 0xffff0000, v15
	v_pk_add_f32 v[38:39], v[14:15], v[38:39] neg_lo:[0,1] neg_hi:[0,1]
	v_div_scale_f32 v37, vcc, 1.0, v34, 1.0
	v_pk_add_f32 v[32:33], v[32:33], v[38:39]
	v_fma_f32 v38, -v35, v36, 1.0
	v_fmac_f32_e32 v36, v38, v36
	v_mul_f32_e32 v38, v37, v36
	v_fma_f32 v39, -v35, v38, v37
	v_fmac_f32_e32 v38, v39, v36
	v_fma_f32 v35, -v35, v38, v37
	v_pk_add_f32 v[24:25], v[40:41], v[24:25] neg_lo:[0,1] neg_hi:[0,1]
	v_div_fmas_f32 v35, v35, v36, v38
	s_add_i32 s62, s10, 2
	v_pk_add_f32 v[26:27], v[26:27], v[24:25]
	v_div_fixup_f32 v34, v35, v34, 1.0
	s_ashr_i32 s63, s62, 31
	v_fma_f32 v35, v34, v26, -v40
	v_fma_f32 v36, v34, v27, -v41
	v_fma_f32 v12, v34, v28, -v12
	v_fma_f32 v13, v34, v29, -v13
	v_fma_f32 v37, v34, v30, -v50
	v_fma_f32 v38, v34, v31, -v51
	v_fma_f32 v14, v34, v32, -v14
	v_fma_f32 v15, v34, v33, -v15
	s_lshl_b64 s[64:65], s[62:63], 13
	v_mul_f32_e32 v34, v4, v35
	v_mul_f32_e32 v35, v5, v36
	v_mul_f32_e32 v12, v6, v12
	v_mul_f32_e32 v13, v7, v13
	v_mul_f32_e32 v36, v8, v37
	v_mul_f32_e32 v37, v9, v38
	v_mul_f32_e32 v14, v10, v14
	v_mul_f32_e32 v15, v11, v15
	v_lshl_add_u64 v[24:25], v[16:17], 0, s[64:65]
	v_cmp_ge_i32_e32 vcc, s11, v43
	s_waitcnt vmcnt(0)
	v_lshlrev_b32_e32 v38, 16, v46
	v_and_b32_e32 v39, 0xffff0000, v46
	v_lshlrev_b32_e32 v40, 16, v47
	v_and_b32_e32 v41, 0xffff0000, v47
	v_lshlrev_b32_e32 v46, 16, v48
	v_and_b32_e32 v47, 0xffff0000, v48
	v_lshlrev_b32_e32 v48, 16, v49
	v_and_b32_e32 v49, 0xffff0000, v49
	v_mul_f32_e32 v34, v34, v38
	v_mul_f32_e32 v35, v35, v39
	v_mul_f32_e32 v12, v12, v40
	v_mul_f32_e32 v13, v13, v41
	v_mul_f32_e32 v36, v36, v46
	v_mul_f32_e32 v37, v37, v47
	v_mul_f32_e32 v14, v14, v48
	v_mul_f32_e32 v15, v15, v49
	v_cvt_pk_bf16_f32 v34, v34, v35
	v_cvt_pk_bf16_f32 v35, v12, v13
	v_cvt_pk_bf16_f32 v36, v36, v37
	v_cvt_pk_bf16_f32 v37, v14, v15
	global_load_dwordx4 v[12:15], v[24:25], off
	v_lshl_add_u64 v[24:25], v[18:19], 0, s[60:61]
	global_store_dwordx4 v[24:25], v[34:37], off
	v_mov_b32_e32 v24, 0
	v_mov_b32_e32 v38, 0
	v_mov_b32_e32 v34, 0
	v_mov_b32_e32 v35, 0
	v_mov_b32_e32 v36, 0
	v_mov_b32_e32 v37, 0
	v_mov_b32_e32 v39, 0
	v_mov_b32_e32 v40, 0
	v_mov_b32_e32 v41, 0
	s_and_saveexec_b64 s[60:61], vcc
	s_cbranch_execz .LBB0_323
	v_add3_u32 v34, v45, s25, 2
	v_ashrrev_i32_e32 v35, 31, v34
	v_lshlrev_b64 v[34:35], 13, v[34:35]
	v_lshl_add_u64 v[34:35], v[16:17], 0, v[34:35]
	global_load_dwordx4 v[38:41], v[34:35], off
	s_waitcnt vmcnt(0)
	v_lshlrev_b32_e32 v34, 16, v38
	v_and_b32_e32 v35, 0xffff0000, v38
	v_lshlrev_b32_e32 v36, 16, v39
	v_and_b32_e32 v37, 0xffff0000, v39
	v_lshlrev_b32_e32 v38, 16, v40
	v_and_b32_e32 v39, 0xffff0000, v40
	v_lshlrev_b32_e32 v40, 16, v41
	v_and_b32_e32 v41, 0xffff0000, v41
.LBB0_323:
	s_or_b64 exec, exec, s[60:61]
	s_lshl_b64 s[60:61], s[62:63], 12
	s_lshl_b64 s[60:61], s[60:61], 1
	v_lshl_add_u64 v[46:47], v[20:21], 0, s[60:61]
	global_load_dwordx4 v[46:49], v[46:47], off
	s_add_i32 s34, s33, 3
	v_cvt_f32_u32_e32 v25, s34
	s_waitcnt vmcnt(2)
	v_lshlrev_b32_e32 v50, 16, v12
	v_and_b32_e32 v51, 0xffff0000, v12
	v_cmp_lt_i32_e32 vcc, s34, v43
	v_pk_add_f32 v[34:35], v[50:51], v[34:35] neg_lo:[0,1] neg_hi:[0,1]
	v_lshlrev_b32_e32 v12, 16, v13
	v_cndmask_b32_e32 v25, v44, v25, vcc
	v_pk_add_f32 v[26:27], v[26:27], v[34:35]
	v_div_scale_f32 v34, s[64:65], v25, v25, 1.0
	v_rcp_f32_e32 v35, v34
	v_and_b32_e32 v13, 0xffff0000, v13
	v_pk_add_f32 v[36:37], v[12:13], v[36:37] neg_lo:[0,1] neg_hi:[0,1]
	v_lshlrev_b32_e32 v52, 16, v14
	v_pk_add_f32 v[28:29], v[28:29], v[36:37]
	v_fma_f32 v37, -v34, v35, 1.0
	v_and_b32_e32 v53, 0xffff0000, v14
	v_lshlrev_b32_e32 v14, 16, v15
	v_and_b32_e32 v15, 0xffff0000, v15
	v_div_scale_f32 v36, vcc, 1.0, v25, 1.0
	v_fmac_f32_e32 v35, v37, v35
	v_pk_add_f32 v[40:41], v[14:15], v[40:41] neg_lo:[0,1] neg_hi:[0,1]
	v_mul_f32_e32 v37, v36, v35
	v_pk_add_f32 v[32:33], v[32:33], v[40:41]
	v_fma_f32 v40, -v34, v37, v36
	v_fmac_f32_e32 v37, v40, v35
	v_fma_f32 v34, -v34, v37, v36
	v_pk_add_f32 v[38:39], v[52:53], v[38:39] neg_lo:[0,1] neg_hi:[0,1]
	v_div_fmas_f32 v34, v34, v35, v37
	s_add_i32 s10, s10, 3
	v_pk_add_f32 v[30:31], v[30:31], v[38:39]
	v_div_fixup_f32 v25, v34, v25, 1.0
	s_ashr_i32 s11, s10, 31
	v_fma_f32 v34, v25, v26, -v50
	v_fma_f32 v35, v25, v27, -v51
	v_fma_f32 v12, v25, v28, -v12
	v_fma_f32 v13, v25, v29, -v13
	v_fma_f32 v36, v25, v30, -v52
	v_fma_f32 v37, v25, v31, -v53
	v_fma_f32 v14, v25, v32, -v14
	v_fma_f32 v15, v25, v33, -v15
	s_lshl_b64 s[62:63], s[10:11], 13
	v_mul_f32_e32 v25, v4, v34
	v_mul_f32_e32 v34, v5, v35
	v_mul_f32_e32 v12, v6, v12
	v_mul_f32_e32 v13, v7, v13
	v_mul_f32_e32 v35, v8, v36
	v_mul_f32_e32 v36, v9, v37
	v_mul_f32_e32 v14, v10, v14
	v_mul_f32_e32 v15, v11, v15
	v_lshl_add_u64 v[38:39], v[16:17], 0, s[62:63]
	v_cmp_ge_i32_e32 vcc, s34, v43
	s_waitcnt vmcnt(0)
	v_lshlrev_b32_e32 v37, 16, v46
	v_and_b32_e32 v40, 0xffff0000, v46
	v_lshlrev_b32_e32 v41, 16, v47
	v_and_b32_e32 v46, 0xffff0000, v47
	v_lshlrev_b32_e32 v47, 16, v48
	v_and_b32_e32 v48, 0xffff0000, v48
	v_lshlrev_b32_e32 v50, 16, v49
	v_and_b32_e32 v49, 0xffff0000, v49
	v_mul_f32_e32 v25, v25, v37
	v_mul_f32_e32 v34, v34, v40
	v_mul_f32_e32 v12, v12, v41
	v_mul_f32_e32 v13, v13, v46
	v_mul_f32_e32 v37, v35, v47
	v_mul_f32_e32 v36, v36, v48
	v_mul_f32_e32 v14, v14, v50
	v_mul_f32_e32 v15, v15, v49
	v_cvt_pk_bf16_f32 v34, v25, v34
	v_cvt_pk_bf16_f32 v35, v12, v13
	v_cvt_pk_bf16_f32 v36, v37, v36
	v_cvt_pk_bf16_f32 v37, v14, v15
	global_load_dwordx4 v[12:15], v[38:39], off
	v_lshl_add_u64 v[38:39], v[18:19], 0, s[60:61]
	global_store_dwordx4 v[38:39], v[34:37], off
	v_mov_b32_e32 v25, 0
	v_mov_b32_e32 v38, 0
	v_mov_b32_e32 v34, 0
	v_mov_b32_e32 v35, 0
	v_mov_b32_e32 v36, 0
	v_mov_b32_e32 v37, 0
	v_mov_b32_e32 v39, 0
	s_and_saveexec_b64 s[60:61], vcc
	s_cbranch_execz .LBB0_316
	v_add3_u32 v24, v45, s25, 3
	v_ashrrev_i32_e32 v25, 31, v24
	v_lshlrev_b64 v[24:25], 13, v[24:25]
	v_lshl_add_u64 v[24:25], v[16:17], 0, v[24:25]
	global_load_dwordx4 v[36:39], v[24:25], off
	s_waitcnt vmcnt(0)
	v_lshlrev_b32_e32 v24, 16, v36
	v_and_b32_e32 v25, 0xffff0000, v36
	v_lshlrev_b32_e32 v34, 16, v37
	v_and_b32_e32 v35, 0xffff0000, v37
	v_lshlrev_b32_e32 v36, 16, v38
	v_and_b32_e32 v37, 0xffff0000, v38
	v_lshlrev_b32_e32 v38, 16, v39
	v_and_b32_e32 v39, 0xffff0000, v39
	s_branch .LBB0_316
